# K-loop LDS-DMA loads converted to SGPR-base+32bit-voffset form (no VALU address adds) in all three GEMM loops
# speedup vs baseline: 1.0067x; 1.0067x over previous
; #define PG8_STAGE(bufoff, gbase, voff) do { _Pragma("unroll") for (int _i = 0; _i < 2; ++_i) \
;         __builtin_amdgcn_global_load_lds((const unsigned*)((const char*)(gbase) + (voff)[_i]), (PG8_LAS unsigned*)(lds + (bufoff) + ldsw + _i * 8192), 16, 0, 0); } while (0)
; #define PG8_LDA(dst, b, h) do { _Pragma("unroll") for (int m = 0; m < 4; ++m) _Pragma("unroll") for (int k = 0; k < 2; ++k) dst[m][k] = *(const PG8_LAS bf16x8*)(lds + PG8_SA(b, h) + aoff + m * 2048 + k * 1024); } while (0)
; #define PG8_LDB(dst, b, h) do { _Pragma("unroll") for (int n = 0; n < 2; ++n) _Pragma("unroll") for (int k = 0; k < 2; ++k) dst[n][k] = *(const PG8_LAS bf16x8*)(lds + PG8_SB(b, h) + boff + n * 2048 + k * 1024); } while (0)
; #define PG8_MMA(ai, bj, At, Bt) do { __builtin_amdgcn_s_setprio(1); _Pragma("unroll") for (int m = 0; m < 4; ++m) _Pragma("unroll") for (int n = 0; n < 2; ++n) _Pragma("unroll") for (int k = 0; k < 2; ++k) \
;         acc[ai][bj][m][n] = __builtin_amdgcn_mfma_f32_16x16x32_bf16(Bt[n][k], At[m][k], acc[ai][bj][m][n], 0, 0, 0); __builtin_amdgcn_s_setprio(0); } while (0)
; #define PG8_WAIT_V(n) asm volatile("s_waitcnt vmcnt(" #n ")" ::: "memory")
; #define PG8_BAR __builtin_amdgcn_s_barrier()
; template <class Epi, class Sched, bool ALIGN_EPI = false, bool SP2 = false>
; __device__ __forceinline__ void gemm_phase(PG8_LAS unsigned char* lds, const Gemm g, const Sched& S, const Epi& E) {
;     ...
;         for (int t = 0; t < nt; t += 2) {
;             const bool last = (t == nt - 2);
;             const char* a1 = cA + (size_t)(t + 1) * kstep;
;             const char* a2 = last ? nA : cA + (size_t)(t + 2) * kstep; const char* b2 = last ? nB : cB + (size_t)(t + 2) * kstep;
;             const char* a3 = a2 + kstep; const char* b3 = b2 + kstep;
;             if (last && has_next) S.a_ready(nxt);
;             if constexpr (SP2) {
;             PG8_LDB(B0, 0, 0); PG8_LDB(B1, 0, 1); PG8_SCHED; PG8_LDA(At, 0, 0); PG8_STAGE(PG8_SA(1, 1), a1 + hstep, voffA);
;             PG8_WAIT_V(8); PG8_WAIT_L(0); PG8_BAR; PG8_MMA(0, 0, At, B0); PG8_MMA(0, 1, At, B1); PG8_BAR; PG8_SCHED;
;             PG8_LDA(At, 0, 1); PG8_STAGE(PG8_SB(0, 0), b2, voffB); PG8_STAGE(PG8_SB(0, 1), b2 + hstep, voffB); PG8_STAGE(PG8_SA(0, 0), a2, voffA);
;             PG8_WAIT_V(8); PG8_WAIT_L(0); PG8_BAR; PG8_MMA(1, 0, At, B0); PG8_MMA(1, 1, At, B1); PG8_BAR; PG8_SCHED;
.LBB0_95:
	s_add_u32 s2, s50, 0xfff80080
	s_addc_u32 s3, s51, -1
	s_add_i32 s20, 0, 0x10000
	s_cmp_eq_u32 s67, 28
	s_cselect_b32 s53, s45, s3
	s_cselect_b32 s52, s61, s2
	s_cselect_b32 s25, s43, s66
	s_cselect_b32 s24, s64, s65
	s_add_i32 s33, 0, 0x14000
	v_add_u32_e32 v126, s20, v163
	v_add_u32_e32 v160, s33, v163
	ds_read_b128 v[114:117], v126
	ds_read_b128 v[118:121], v126 offset:1024
	ds_read_b128 v[122:125], v126 offset:2048
	ds_read_b128 v[126:129], v126 offset:3072
	ds_read_b128 v[156:159], v160
	ds_read_b128 v[166:169], v160 offset:1024
	ds_read_b128 v[170:173], v160 offset:2048
	ds_read_b128 v[174:177], v160 offset:3072
	s_add_i32 m0, s7, 0xc000
	ds_read_b128 v[186:189], v165
	ds_read_b128 v[190:193], v165 offset:1024
	ds_read_b128 v[194:197], v165 offset:2048
	ds_read_b128 v[198:201], v165 offset:3072
	ds_read_b128 v[202:205], v165 offset:4096
	ds_read_b128 v[206:209], v165 offset:5120
	ds_read_b128 v[210:213], v165 offset:6144
	ds_read_b128 v[214:217], v165 offset:7168
	global_load_lds_dwordx4 v154, s[50:51]
	s_add_i32 m0, s7, 0xe000
	s_nop 0
	global_load_lds_dwordx4 v152, s[50:51]
	s_waitcnt vmcnt(8)
	s_waitcnt lgkmcnt(0)
	s_barrier
	s_setprio 1
	s_waitcnt lgkmcnt(0)
	v_mfma_f32_16x16x32_bf16 v[142:145], v[114:117], v[186:189], v[142:145]
	v_mfma_f32_16x16x32_bf16 v[138:141], v[122:125], v[186:189], v[138:141]
	v_mfma_f32_16x16x32_bf16 v[110:113], v[114:117], v[194:197], v[110:113]
	v_mfma_f32_16x16x32_bf16 v[106:109], v[122:125], v[194:197], v[106:109]
	v_mfma_f32_16x16x32_bf16 v[94:97], v[114:117], v[202:205], v[94:97]
	v_mfma_f32_16x16x32_bf16 v[90:93], v[122:125], v[202:205], v[90:93]
	v_mfma_f32_16x16x32_bf16 v[86:89], v[114:117], v[210:213], v[86:89]
	v_mfma_f32_16x16x32_bf16 v[78:81], v[122:125], v[210:213], v[78:81]
	v_mfma_f32_16x16x32_bf16 v[142:145], v[118:121], v[190:193], v[142:145]
	v_mfma_f32_16x16x32_bf16 v[138:141], v[126:129], v[190:193], v[138:141]
	v_mfma_f32_16x16x32_bf16 v[110:113], v[118:121], v[198:201], v[110:113]
	v_mfma_f32_16x16x32_bf16 v[106:109], v[126:129], v[198:201], v[106:109]
	v_mfma_f32_16x16x32_bf16 v[94:97], v[118:121], v[206:209], v[94:97]
	v_mfma_f32_16x16x32_bf16 v[90:93], v[126:129], v[206:209], v[90:93]
	v_mfma_f32_16x16x32_bf16 v[86:89], v[118:121], v[214:217], v[86:89]
	v_mfma_f32_16x16x32_bf16 v[78:81], v[126:129], v[214:217], v[78:81]
	s_setprio 0
	s_setprio 1
	v_mfma_f32_16x16x32_bf16 v[134:137], v[156:159], v[186:189], v[134:137]
	v_mfma_f32_16x16x32_bf16 v[130:133], v[170:173], v[186:189], v[130:133]
	v_mfma_f32_16x16x32_bf16 v[102:105], v[156:159], v[194:197], v[102:105]
	v_mfma_f32_16x16x32_bf16 v[98:101], v[170:173], v[194:197], v[98:101]
	v_mfma_f32_16x16x32_bf16 v[82:85], v[156:159], v[202:205], v[82:85]
	v_mfma_f32_16x16x32_bf16 v[74:77], v[170:173], v[202:205], v[74:77]
	v_mfma_f32_16x16x32_bf16 v[70:73], v[156:159], v[210:213], v[70:73]
	v_mfma_f32_16x16x32_bf16 v[66:69], v[170:173], v[210:213], v[66:69]
	v_mfma_f32_16x16x32_bf16 v[134:137], v[166:169], v[190:193], v[134:137]
	v_mfma_f32_16x16x32_bf16 v[130:133], v[174:177], v[190:193], v[130:133]
	v_mfma_f32_16x16x32_bf16 v[102:105], v[166:169], v[198:201], v[102:105]
	v_mfma_f32_16x16x32_bf16 v[98:101], v[174:177], v[198:201], v[98:101]
	v_mfma_f32_16x16x32_bf16 v[82:85], v[166:169], v[206:209], v[82:85]
	v_mfma_f32_16x16x32_bf16 v[74:77], v[174:177], v[206:209], v[74:77]
	v_mfma_f32_16x16x32_bf16 v[70:73], v[166:169], v[214:217], v[70:73]
	v_mfma_f32_16x16x32_bf16 v[66:69], v[174:177], v[214:217], v[66:69]
	s_setprio 0
	s_barrier
	s_add_i32 s2, s20, s6
	s_mov_b32 m0, s2
	ds_read_b128 v[186:189], v165 offset:16384
	ds_read_b128 v[190:193], v165 offset:17408
	ds_read_b128 v[194:197], v165 offset:18432
	ds_read_b128 v[198:201], v165 offset:19456
	ds_read_b128 v[202:205], v165 offset:20480
	ds_read_b128 v[206:209], v165 offset:21504
	ds_read_b128 v[210:213], v165 offset:22528
	ds_read_b128 v[214:217], v165 offset:23552
	global_load_lds_dwordx4 v0, s[24:25]
	s_add_i32 m0, s2, 0x2000
	s_add_u32 s2, s24, 0x80000
	s_addc_u32 s3, s25, 0
	s_add_i32 s20, s33, s6
	global_load_lds_dwordx4 v146, s[24:25]
	s_mov_b32 m0, s20
	s_nop 0
	global_load_lds_dwordx4 v0, s[2:3]
	s_add_i32 m0, s20, 0x2000
	s_nop 0
	global_load_lds_dwordx4 v146, s[2:3]
	s_mov_b32 m0, s7
	s_nop 0
	global_load_lds_dwordx4 v150, s[52:53]
	s_mov_b32 m0, s8
	s_nop 0
	global_load_lds_dwordx4 v148, s[52:53]
	s_waitcnt vmcnt(8)
	s_waitcnt lgkmcnt(0)
	s_barrier
	s_setprio 1
	s_waitcnt lgkmcnt(0)
	v_mfma_f32_16x16x32_bf16 v[62:65], v[114:117], v[186:189], v[62:65]
	v_mfma_f32_16x16x32_bf16 v[58:61], v[122:125], v[186:189], v[58:61]
	v_mfma_f32_16x16x32_bf16 v[54:57], v[114:117], v[194:197], v[54:57]
	v_mfma_f32_16x16x32_bf16 v[50:53], v[122:125], v[194:197], v[50:53]
	v_mfma_f32_16x16x32_bf16 v[38:41], v[114:117], v[202:205], v[38:41]
	v_mfma_f32_16x16x32_bf16 v[34:37], v[122:125], v[202:205], v[34:37]
	v_mfma_f32_16x16x32_bf16 v[22:25], v[114:117], v[210:213], v[22:25]
	v_mfma_f32_16x16x32_bf16 v[18:21], v[122:125], v[210:213], v[18:21]
	v_mfma_f32_16x16x32_bf16 v[62:65], v[118:121], v[190:193], v[62:65]
	v_mfma_f32_16x16x32_bf16 v[58:61], v[126:129], v[190:193], v[58:61]
	v_mfma_f32_16x16x32_bf16 v[54:57], v[118:121], v[198:201], v[54:57]
	v_mfma_f32_16x16x32_bf16 v[50:53], v[126:129], v[198:201], v[50:53]
	v_mfma_f32_16x16x32_bf16 v[38:41], v[118:121], v[206:209], v[38:41]
	v_mfma_f32_16x16x32_bf16 v[34:37], v[126:129], v[206:209], v[34:37]
	v_mfma_f32_16x16x32_bf16 v[22:25], v[118:121], v[214:217], v[22:25]
	v_mfma_f32_16x16x32_bf16 v[18:21], v[126:129], v[214:217], v[18:21]
	s_setprio 0
	s_setprio 1
	v_mfma_f32_16x16x32_bf16 v[46:49], v[156:159], v[186:189], v[46:49]
	v_mfma_f32_16x16x32_bf16 v[42:45], v[170:173], v[186:189], v[42:45]
	v_mfma_f32_16x16x32_bf16 v[30:33], v[156:159], v[194:197], v[30:33]
	v_mfma_f32_16x16x32_bf16 v[26:29], v[170:173], v[194:197], v[26:29]
	v_mfma_f32_16x16x32_bf16 v[14:17], v[156:159], v[202:205], v[14:17]
	v_mfma_f32_16x16x32_bf16 v[10:13], v[170:173], v[202:205], v[10:13]
	v_mfma_f32_16x16x32_bf16 v[6:9], v[156:159], v[210:213], v[6:9]
	v_mfma_f32_16x16x32_bf16 v[2:5], v[170:173], v[210:213], v[2:5]
	v_mfma_f32_16x16x32_bf16 v[46:49], v[166:169], v[190:193], v[46:49]
	v_mfma_f32_16x16x32_bf16 v[42:45], v[174:177], v[190:193], v[42:45]
	v_mfma_f32_16x16x32_bf16 v[30:33], v[166:169], v[198:201], v[30:33]
	v_mfma_f32_16x16x32_bf16 v[26:29], v[174:177], v[198:201], v[26:29]
	v_mfma_f32_16x16x32_bf16 v[14:17], v[166:169], v[206:209], v[14:17]
	v_mfma_f32_16x16x32_bf16 v[10:13], v[174:177], v[206:209], v[10:13]
	v_mfma_f32_16x16x32_bf16 v[6:9], v[166:169], v[214:217], v[6:9]
	v_mfma_f32_16x16x32_bf16 v[2:5], v[174:177], v[214:217], v[2:5]
	s_setprio 0
	s_barrier
; #define PG8_STAGE(bufoff, gbase, voff) do { _Pragma("unroll") for (int _i = 0; _i < 2; ++_i) \
;         __builtin_amdgcn_global_load_lds((const unsigned*)((const char*)(gbase) + (voff)[_i]), (PG8_LAS unsigned*)(lds + (bufoff) + ldsw + _i * 8192), 16, 0, 0); } while (0)
; #define PG8_LDA(dst, b, h) do { _Pragma("unroll") for (int m = 0; m < 4; ++m) _Pragma("unroll") for (int k = 0; k < 2; ++k) dst[m][k] = *(const PG8_LAS bf16x8*)(lds + PG8_SA(b, h) + aoff + m * 2048 + k * 1024); } while (0)
; #define PG8_LDB(dst, b, h) do { _Pragma("unroll") for (int n = 0; n < 2; ++n) _Pragma("unroll") for (int k = 0; k < 2; ++k) dst[n][k] = *(const PG8_LAS bf16x8*)(lds + PG8_SB(b, h) + boff + n * 2048 + k * 1024); } while (0)
; #define PG8_MMA(ai, bj, At, Bt) do { __builtin_amdgcn_s_setprio(1); _Pragma("unroll") for (int m = 0; m < 4; ++m) _Pragma("unroll") for (int n = 0; n < 2; ++n) _Pragma("unroll") for (int k = 0; k < 2; ++k) \
;         acc[ai][bj][m][n] = __builtin_amdgcn_mfma_f32_16x16x32_bf16(Bt[n][k], At[m][k], acc[ai][bj][m][n], 0, 0, 0); __builtin_amdgcn_s_setprio(0); } while (0)
; #define PG8_WAIT_V(n) asm volatile("s_waitcnt vmcnt(" #n ")" ::: "memory")
; #define PG8_WAIT_L(n) asm volatile("s_waitcnt lgkmcnt(" #n ")" ::: "memory")
; #define PG8_BAR __builtin_amdgcn_s_barrier()
; #define PG8_SCHED __builtin_amdgcn_sched_barrier(0)
; template <class Epi, class Sched, bool ALIGN_EPI = false, bool SP2 = false>
; __device__ __forceinline__ void gemm_phase(PG8_LAS unsigned char* lds, const Gemm g, const Sched& S, const Epi& E) {
;     ...
;             PG8_LDB(B0, 1, 0); PG8_LDB(B1, 1, 1); PG8_SCHED; PG8_LDA(At, 1, 0); PG8_STAGE(PG8_SA(0, 1), a2 + hstep, voffA);
;             PG8_WAIT_V(8); PG8_WAIT_L(0); PG8_BAR; PG8_MMA(0, 0, At, B0); PG8_MMA(0, 1, At, B1); PG8_BAR; PG8_SCHED;
;             PG8_LDA(At, 1, 1); PG8_STAGE(PG8_SB(1, 0), b3, voffB); PG8_STAGE(PG8_SB(1, 1), b3 + hstep, voffB); PG8_STAGE(PG8_SA(1, 0), a3, voffA);
;             PG8_WAIT_V(8); PG8_WAIT_L(0); PG8_BAR; PG8_MMA(1, 0, At, B0); PG8_MMA(1, 1, At, B1); PG8_BAR; PG8_SCHED;
	s_add_i32 s20, 0, 0x18000
	s_add_i32 s33, 0, 0x1c000
	v_add_u32_e32 v126, s20, v163
	v_add_u32_e32 v174, s33, v163
	ds_read_b128 v[114:117], v126
	ds_read_b128 v[118:121], v126 offset:1024
	ds_read_b128 v[122:125], v126 offset:2048
	ds_read_b128 v[126:129], v126 offset:3072
	ds_read_b128 v[156:159], v174
	ds_read_b128 v[166:169], v174 offset:1024
	ds_read_b128 v[170:173], v174 offset:2048
	ds_read_b128 v[174:177], v174 offset:3072
	s_add_u32 s2, s52, 0x80000
	s_addc_u32 s3, s53, 0
	s_mov_b32 m0, s9
	ds_read_b128 v[186:189], v165 offset:32768
	ds_read_b128 v[190:193], v165 offset:33792
	ds_read_b128 v[194:197], v165 offset:34816
	ds_read_b128 v[198:201], v165 offset:35840
	ds_read_b128 v[202:205], v165 offset:36864
	ds_read_b128 v[206:209], v165 offset:37888
	ds_read_b128 v[210:213], v165 offset:38912
	ds_read_b128 v[214:217], v165 offset:39936
	global_load_lds_dwordx4 v150, s[2:3]
	s_mov_b32 m0, s30
	s_nop 0
	global_load_lds_dwordx4 v148, s[2:3]
	s_waitcnt vmcnt(8)
	s_waitcnt lgkmcnt(0)
	s_barrier
	s_setprio 1
	s_waitcnt lgkmcnt(0)
	v_mfma_f32_16x16x32_bf16 v[142:145], v[114:117], v[186:189], v[142:145]
	v_mfma_f32_16x16x32_bf16 v[138:141], v[122:125], v[186:189], v[138:141]
	v_mfma_f32_16x16x32_bf16 v[110:113], v[114:117], v[194:197], v[110:113]
	v_mfma_f32_16x16x32_bf16 v[106:109], v[122:125], v[194:197], v[106:109]
	v_mfma_f32_16x16x32_bf16 v[94:97], v[114:117], v[202:205], v[94:97]
	v_mfma_f32_16x16x32_bf16 v[90:93], v[122:125], v[202:205], v[90:93]
	v_mfma_f32_16x16x32_bf16 v[86:89], v[114:117], v[210:213], v[86:89]
	v_mfma_f32_16x16x32_bf16 v[78:81], v[122:125], v[210:213], v[78:81]
	v_mfma_f32_16x16x32_bf16 v[142:145], v[118:121], v[190:193], v[142:145]
	v_mfma_f32_16x16x32_bf16 v[138:141], v[126:129], v[190:193], v[138:141]
	v_mfma_f32_16x16x32_bf16 v[110:113], v[118:121], v[198:201], v[110:113]
	v_mfma_f32_16x16x32_bf16 v[106:109], v[126:129], v[198:201], v[106:109]
	v_mfma_f32_16x16x32_bf16 v[94:97], v[118:121], v[206:209], v[94:97]
	v_mfma_f32_16x16x32_bf16 v[90:93], v[126:129], v[206:209], v[90:93]
	v_mfma_f32_16x16x32_bf16 v[86:89], v[118:121], v[214:217], v[86:89]
	v_mfma_f32_16x16x32_bf16 v[78:81], v[126:129], v[214:217], v[78:81]
	s_setprio 0
	s_setprio 1
	v_mfma_f32_16x16x32_bf16 v[134:137], v[156:159], v[186:189], v[134:137]
	v_mfma_f32_16x16x32_bf16 v[130:133], v[170:173], v[186:189], v[130:133]
	v_mfma_f32_16x16x32_bf16 v[102:105], v[156:159], v[194:197], v[102:105]
	v_mfma_f32_16x16x32_bf16 v[98:101], v[170:173], v[194:197], v[98:101]
	v_mfma_f32_16x16x32_bf16 v[82:85], v[156:159], v[202:205], v[82:85]
	v_mfma_f32_16x16x32_bf16 v[74:77], v[170:173], v[202:205], v[74:77]
	v_mfma_f32_16x16x32_bf16 v[70:73], v[156:159], v[210:213], v[70:73]
	v_mfma_f32_16x16x32_bf16 v[66:69], v[170:173], v[210:213], v[66:69]
	v_mfma_f32_16x16x32_bf16 v[134:137], v[166:169], v[190:193], v[134:137]
	v_mfma_f32_16x16x32_bf16 v[130:133], v[174:177], v[190:193], v[130:133]
	v_mfma_f32_16x16x32_bf16 v[102:105], v[166:169], v[198:201], v[102:105]
	v_mfma_f32_16x16x32_bf16 v[98:101], v[174:177], v[198:201], v[98:101]
	v_mfma_f32_16x16x32_bf16 v[82:85], v[166:169], v[206:209], v[82:85]
	v_mfma_f32_16x16x32_bf16 v[74:77], v[174:177], v[206:209], v[74:77]
	v_mfma_f32_16x16x32_bf16 v[70:73], v[166:169], v[214:217], v[70:73]
	v_mfma_f32_16x16x32_bf16 v[66:69], v[174:177], v[214:217], v[66:69]
	s_setprio 0
	s_barrier
	s_add_i32 s2, s20, s6
	s_add_i32 m0, s2, 0xffffff80
	ds_read_b128 v[186:189], v165 offset:49152
	ds_read_b128 v[190:193], v165 offset:50176
	ds_read_b128 v[194:197], v165 offset:51200
	ds_read_b128 v[198:201], v165 offset:52224
	ds_read_b128 v[202:205], v165 offset:53248
	ds_read_b128 v[206:209], v165 offset:54272
	ds_read_b128 v[210:213], v165 offset:55296
	ds_read_b128 v[214:217], v165 offset:56320
	global_load_lds_dwordx4 v0, s[24:25] offset:128
	s_add_i32 m0, s2, 0x1f80
	s_add_u32 s2, s24, 0x80080
	s_addc_u32 s3, s25, 0
	s_add_i32 s20, s33, s6
	global_load_lds_dwordx4 v146, s[24:25] offset:128
	s_mov_b32 m0, s20
	s_nop 0
	global_load_lds_dwordx4 v0, s[2:3]
	s_add_i32 m0, s20, 0x2000
	s_nop 0
	global_load_lds_dwordx4 v146, s[2:3]
	s_add_i32 m0, s56, 0xffffff80
	s_nop 0
	global_load_lds_dwordx4 v150, s[52:53] offset:128
	s_add_i32 m0, s57, 0xffffff80
	s_nop 0
	global_load_lds_dwordx4 v148, s[52:53] offset:128
	s_waitcnt vmcnt(8)
	s_waitcnt lgkmcnt(0)
	s_barrier
	s_setprio 1
	s_waitcnt lgkmcnt(0)
	v_mfma_f32_16x16x32_bf16 v[62:65], v[114:117], v[186:189], v[62:65]
	v_mfma_f32_16x16x32_bf16 v[58:61], v[122:125], v[186:189], v[58:61]
	v_mfma_f32_16x16x32_bf16 v[54:57], v[114:117], v[194:197], v[54:57]
	v_mfma_f32_16x16x32_bf16 v[50:53], v[122:125], v[194:197], v[50:53]
	v_mfma_f32_16x16x32_bf16 v[38:41], v[114:117], v[202:205], v[38:41]
	v_mfma_f32_16x16x32_bf16 v[34:37], v[122:125], v[202:205], v[34:37]
	v_mfma_f32_16x16x32_bf16 v[22:25], v[114:117], v[210:213], v[22:25]
	v_mfma_f32_16x16x32_bf16 v[18:21], v[122:125], v[210:213], v[18:21]
	v_mfma_f32_16x16x32_bf16 v[62:65], v[118:121], v[190:193], v[62:65]
	v_mfma_f32_16x16x32_bf16 v[58:61], v[126:129], v[190:193], v[58:61]
	v_mfma_f32_16x16x32_bf16 v[54:57], v[118:121], v[198:201], v[54:57]
	v_mfma_f32_16x16x32_bf16 v[50:53], v[126:129], v[198:201], v[50:53]
	v_mfma_f32_16x16x32_bf16 v[38:41], v[118:121], v[206:209], v[38:41]
	v_mfma_f32_16x16x32_bf16 v[34:37], v[126:129], v[206:209], v[34:37]
	v_mfma_f32_16x16x32_bf16 v[22:25], v[118:121], v[214:217], v[22:25]
	v_mfma_f32_16x16x32_bf16 v[18:21], v[126:129], v[214:217], v[18:21]
	s_setprio 0
	s_setprio 1
	v_mfma_f32_16x16x32_bf16 v[46:49], v[156:159], v[186:189], v[46:49]
	v_mfma_f32_16x16x32_bf16 v[42:45], v[170:173], v[186:189], v[42:45]
	v_mfma_f32_16x16x32_bf16 v[30:33], v[156:159], v[194:197], v[30:33]
	v_mfma_f32_16x16x32_bf16 v[26:29], v[170:173], v[194:197], v[26:29]
	v_mfma_f32_16x16x32_bf16 v[14:17], v[156:159], v[202:205], v[14:17]
	v_mfma_f32_16x16x32_bf16 v[10:13], v[170:173], v[202:205], v[10:13]
	v_mfma_f32_16x16x32_bf16 v[6:9], v[156:159], v[210:213], v[6:9]
	v_mfma_f32_16x16x32_bf16 v[2:5], v[170:173], v[210:213], v[2:5]
	v_mfma_f32_16x16x32_bf16 v[46:49], v[166:169], v[190:193], v[46:49]
	v_mfma_f32_16x16x32_bf16 v[42:45], v[174:177], v[190:193], v[42:45]
	v_mfma_f32_16x16x32_bf16 v[30:33], v[166:169], v[198:201], v[30:33]
	v_mfma_f32_16x16x32_bf16 v[26:29], v[174:177], v[198:201], v[26:29]
	v_mfma_f32_16x16x32_bf16 v[14:17], v[166:169], v[206:209], v[14:17]
	v_mfma_f32_16x16x32_bf16 v[10:13], v[174:177], v[206:209], v[10:13]
	v_mfma_f32_16x16x32_bf16 v[6:9], v[166:169], v[214:217], v[6:9]
	v_mfma_f32_16x16x32_bf16 v[2:5], v[174:177], v[214:217], v[2:5]
	s_setprio 0
	s_barrier
	s_add_i32 s67, s67, 2
	s_add_u32 s65, s65, 0x100
	s_addc_u32 s66, s66, 0
	s_add_u32 s50, s50, 0x100
	s_addc_u32 s51, s51, 0
	s_cmp_gt_u32 s67, 29
	s_cbranch_scc0 .LBB0_95
	s_and_b64 vcc, exec, s[26:27]
	s_cbranch_vccz .LBB0_98
	s_barrier

; #define PG8_STAGE(bufoff, gbase, voff) do { _Pragma("unroll") for (int _i = 0; _i < 2; ++_i) \
;         __builtin_amdgcn_global_load_lds((const unsigned*)((const char*)(gbase) + (voff)[_i]), (PG8_LAS unsigned*)(lds + (bufoff) + ldsw + _i * 8192), 16, 0, 0); } while (0)
; #define PG8_LDA(dst, b, h) do { _Pragma("unroll") for (int m = 0; m < 4; ++m) _Pragma("unroll") for (int k = 0; k < 2; ++k) dst[m][k] = *(const PG8_LAS bf16x8*)(lds + PG8_SA(b, h) + aoff + m * 2048 + k * 1024); } while (0)
; #define PG8_LDB(dst, b, h) do { _Pragma("unroll") for (int n = 0; n < 2; ++n) _Pragma("unroll") for (int k = 0; k < 2; ++k) dst[n][k] = *(const PG8_LAS bf16x8*)(lds + PG8_SB(b, h) + boff + n * 2048 + k * 1024); } while (0)
; #define PG8_MMA(ai, bj, At, Bt) do { __builtin_amdgcn_s_setprio(1); _Pragma("unroll") for (int m = 0; m < 4; ++m) _Pragma("unroll") for (int n = 0; n < 2; ++n) _Pragma("unroll") for (int k = 0; k < 2; ++k) \
;         acc[ai][bj][m][n] = __builtin_amdgcn_mfma_f32_16x16x32_bf16(Bt[n][k], At[m][k], acc[ai][bj][m][n], 0, 0, 0); __builtin_amdgcn_s_setprio(0); } while (0)
; #define PG8_WAIT_V(n) asm volatile("s_waitcnt vmcnt(" #n ")" ::: "memory")
; #define PG8_WAIT_L(n) asm volatile("s_waitcnt lgkmcnt(" #n ")" ::: "memory")
; #define PG8_BAR __builtin_amdgcn_s_barrier()
; template <class Epi, class Sched, bool ALIGN_EPI = false, bool SP2 = false>
; __device__ __forceinline__ void gemm_phase(PG8_LAS unsigned char* lds, const Gemm g, const Sched& S, const Epi& E) {
;     ...
;             const char* a1 = cA + (size_t)(t + 1) * kstep;
;             const char* a2 = last ? nA : cA + (size_t)(t + 2) * kstep; const char* b2 = last ? nB : cB + (size_t)(t + 2) * kstep;
;             const char* a3 = a2 + kstep; const char* b3 = b2 + kstep;
;             if (last && has_next) S.a_ready(nxt);
;             if constexpr (SP2) {
;             PG8_LDB(B0, 0, 0); PG8_LDB(B1, 0, 1); PG8_SCHED; PG8_LDA(At, 0, 0); PG8_STAGE(PG8_SA(1, 1), a1 + hstep, voffA);
;             PG8_WAIT_V(8); PG8_WAIT_L(0); PG8_BAR; PG8_MMA(0, 0, At, B0); PG8_MMA(0, 1, At, B1); PG8_BAR; PG8_SCHED;
;             PG8_LDA(At, 0, 1); PG8_STAGE(PG8_SB(0, 0), b2, voffB); PG8_STAGE(PG8_SB(0, 1), b2 + hstep, voffB); PG8_STAGE(PG8_SA(0, 0), a2, voffA);
;             PG8_WAIT_V(8); PG8_WAIT_L(0); PG8_BAR; PG8_MMA(1, 0, At, B0); PG8_MMA(1, 1, At, B1); PG8_BAR; PG8_SCHED;
.LBB0_309:
	s_add_u32 s2, s12, 0xfff80080
	s_addc_u32 s3, s13, -1
	s_add_i32 s20, 0, 0x10000
	s_cmp_eq_u32 s53, 28
	s_cselect_b32 s27, s5, s3
	s_cselect_b32 s26, s6, s2
	v_add_u32_e32 v0, s20, v151
	s_cselect_b32 s25, s7, s30
	s_cselect_b32 s24, s8, s9
	s_add_i32 s33, 0, 0x14000
	ds_read_b128 v[142:145], v0
	s_waitcnt lgkmcnt(0)
	ds_read_b128 v[146:149], v0 offset:1024
	ds_read_b128 v[154:157], v0 offset:2048
	ds_read_b128 v[158:161], v0 offset:3072
	v_add_u32_e32 v0, s33, v151
	ds_read_b128 v[162:165], v0
	ds_read_b128 v[166:169], v0 offset:1024
	ds_read_b128 v[170:173], v0 offset:2048
	ds_read_b128 v[174:177], v0 offset:3072
	s_add_i32 m0, s65, 0xc000
	ds_read_b128 v[186:189], v153
	ds_read_b128 v[190:193], v153 offset:1024
	ds_read_b128 v[194:197], v153 offset:2048
	ds_read_b128 v[198:201], v153 offset:3072
	ds_read_b128 v[202:205], v153 offset:4096
	ds_read_b128 v[206:209], v153 offset:5120
	ds_read_b128 v[210:213], v153 offset:6144
	ds_read_b128 v[214:217], v153 offset:7168
	global_load_lds_dwordx4 v140, s[12:13]
	s_add_i32 m0, s65, 0xe000
	s_nop 0
	global_load_lds_dwordx4 v138, s[12:13]
	s_waitcnt vmcnt(8)
	s_waitcnt lgkmcnt(0)
	s_barrier
	s_setprio 1
	s_waitcnt lgkmcnt(0)
	v_mfma_f32_16x16x32_bf16 v[126:129], v[142:145], v[186:189], v[126:129]
	v_mfma_f32_16x16x32_bf16 v[122:125], v[154:157], v[186:189], v[122:125]
	v_mfma_f32_16x16x32_bf16 v[110:113], v[142:145], v[194:197], v[110:113]
	v_mfma_f32_16x16x32_bf16 v[106:109], v[154:157], v[194:197], v[106:109]
	v_mfma_f32_16x16x32_bf16 v[94:97], v[142:145], v[202:205], v[94:97]
	v_mfma_f32_16x16x32_bf16 v[90:93], v[154:157], v[202:205], v[90:93]
	v_mfma_f32_16x16x32_bf16 v[78:81], v[142:145], v[210:213], v[78:81]
	v_mfma_f32_16x16x32_bf16 v[74:77], v[154:157], v[210:213], v[74:77]
	v_mfma_f32_16x16x32_bf16 v[126:129], v[146:149], v[190:193], v[126:129]
	v_mfma_f32_16x16x32_bf16 v[122:125], v[158:161], v[190:193], v[122:125]
	v_mfma_f32_16x16x32_bf16 v[110:113], v[146:149], v[198:201], v[110:113]
	v_mfma_f32_16x16x32_bf16 v[106:109], v[158:161], v[198:201], v[106:109]
	v_mfma_f32_16x16x32_bf16 v[94:97], v[146:149], v[206:209], v[94:97]
	v_mfma_f32_16x16x32_bf16 v[90:93], v[158:161], v[206:209], v[90:93]
	v_mfma_f32_16x16x32_bf16 v[78:81], v[146:149], v[214:217], v[78:81]
	v_mfma_f32_16x16x32_bf16 v[74:77], v[158:161], v[214:217], v[74:77]
	s_setprio 0
	s_setprio 1
	v_mfma_f32_16x16x32_bf16 v[118:121], v[162:165], v[186:189], v[118:121]
	v_mfma_f32_16x16x32_bf16 v[114:117], v[170:173], v[186:189], v[114:117]
	v_mfma_f32_16x16x32_bf16 v[102:105], v[162:165], v[194:197], v[102:105]
	v_mfma_f32_16x16x32_bf16 v[98:101], v[170:173], v[194:197], v[98:101]
	v_mfma_f32_16x16x32_bf16 v[86:89], v[162:165], v[202:205], v[86:89]
	v_mfma_f32_16x16x32_bf16 v[82:85], v[170:173], v[202:205], v[82:85]
	v_mfma_f32_16x16x32_bf16 v[70:73], v[162:165], v[210:213], v[70:73]
	v_mfma_f32_16x16x32_bf16 v[66:69], v[170:173], v[210:213], v[66:69]
	v_mfma_f32_16x16x32_bf16 v[118:121], v[166:169], v[190:193], v[118:121]
	v_mfma_f32_16x16x32_bf16 v[114:117], v[174:177], v[190:193], v[114:117]
	v_mfma_f32_16x16x32_bf16 v[102:105], v[166:169], v[198:201], v[102:105]
	v_mfma_f32_16x16x32_bf16 v[98:101], v[174:177], v[198:201], v[98:101]
	v_mfma_f32_16x16x32_bf16 v[86:89], v[166:169], v[206:209], v[86:89]
	v_mfma_f32_16x16x32_bf16 v[82:85], v[174:177], v[206:209], v[82:85]
	v_mfma_f32_16x16x32_bf16 v[70:73], v[166:169], v[214:217], v[70:73]
	v_mfma_f32_16x16x32_bf16 v[66:69], v[174:177], v[214:217], v[66:69]
	s_setprio 0
	s_barrier
	s_add_i32 s2, s20, s64
	s_mov_b32 m0, s2
	ds_read_b128 v[186:189], v153 offset:16384
	ds_read_b128 v[190:193], v153 offset:17408
	ds_read_b128 v[194:197], v153 offset:18432
	ds_read_b128 v[198:201], v153 offset:19456
	ds_read_b128 v[202:205], v153 offset:20480
	ds_read_b128 v[206:209], v153 offset:21504
	ds_read_b128 v[210:213], v153 offset:22528
	ds_read_b128 v[214:217], v153 offset:23552
	global_load_lds_dwordx4 v134, s[24:25]
	s_add_i32 m0, s2, 0x2000
	s_add_u32 s2, s24, 0x80000
	s_addc_u32 s3, s25, 0
	s_add_i32 s20, s33, s64
	global_load_lds_dwordx4 v130, s[24:25]
	s_mov_b32 m0, s20
	s_nop 0
	global_load_lds_dwordx4 v134, s[2:3]
	s_add_i32 m0, s20, 0x2000
	s_nop 0
	global_load_lds_dwordx4 v130, s[2:3]
	s_mov_b32 m0, s65
	s_nop 0
	global_load_lds_dwordx4 v136, s[26:27]
	s_mov_b32 m0, s66
	s_nop 0
	global_load_lds_dwordx4 v132, s[26:27]
	s_waitcnt vmcnt(8)
	s_waitcnt lgkmcnt(0)
	s_barrier
	s_setprio 1
	s_waitcnt lgkmcnt(0)
	v_mfma_f32_16x16x32_bf16 v[62:65], v[142:145], v[186:189], v[62:65]
	v_mfma_f32_16x16x32_bf16 v[58:61], v[154:157], v[186:189], v[58:61]
	v_mfma_f32_16x16x32_bf16 v[46:49], v[142:145], v[194:197], v[46:49]
	v_mfma_f32_16x16x32_bf16 v[42:45], v[154:157], v[194:197], v[42:45]
	v_mfma_f32_16x16x32_bf16 v[30:33], v[142:145], v[202:205], v[30:33]
	v_mfma_f32_16x16x32_bf16 v[26:29], v[154:157], v[202:205], v[26:29]
	v_mfma_f32_16x16x32_bf16 v[14:17], v[142:145], v[210:213], v[14:17]
	v_mfma_f32_16x16x32_bf16 v[10:13], v[154:157], v[210:213], v[10:13]
	v_mfma_f32_16x16x32_bf16 v[62:65], v[146:149], v[190:193], v[62:65]
	v_mfma_f32_16x16x32_bf16 v[58:61], v[158:161], v[190:193], v[58:61]
	v_mfma_f32_16x16x32_bf16 v[46:49], v[146:149], v[198:201], v[46:49]
	v_mfma_f32_16x16x32_bf16 v[42:45], v[158:161], v[198:201], v[42:45]
	v_mfma_f32_16x16x32_bf16 v[30:33], v[146:149], v[206:209], v[30:33]
	v_mfma_f32_16x16x32_bf16 v[26:29], v[158:161], v[206:209], v[26:29]
	v_mfma_f32_16x16x32_bf16 v[14:17], v[146:149], v[214:217], v[14:17]
	v_mfma_f32_16x16x32_bf16 v[10:13], v[158:161], v[214:217], v[10:13]
	s_setprio 0
	s_setprio 1
	v_mfma_f32_16x16x32_bf16 v[54:57], v[162:165], v[186:189], v[54:57]
	v_mfma_f32_16x16x32_bf16 v[50:53], v[170:173], v[186:189], v[50:53]
	v_mfma_f32_16x16x32_bf16 v[38:41], v[162:165], v[194:197], v[38:41]
	v_mfma_f32_16x16x32_bf16 v[34:37], v[170:173], v[194:197], v[34:37]
	v_mfma_f32_16x16x32_bf16 v[22:25], v[162:165], v[202:205], v[22:25]
	v_mfma_f32_16x16x32_bf16 v[18:21], v[170:173], v[202:205], v[18:21]
	v_mfma_f32_16x16x32_bf16 v[6:9], v[162:165], v[210:213], v[6:9]
	v_mfma_f32_16x16x32_bf16 v[2:5], v[170:173], v[210:213], v[2:5]
	v_mfma_f32_16x16x32_bf16 v[54:57], v[166:169], v[190:193], v[54:57]
	v_mfma_f32_16x16x32_bf16 v[50:53], v[174:177], v[190:193], v[50:53]
	v_mfma_f32_16x16x32_bf16 v[38:41], v[166:169], v[198:201], v[38:41]
	v_mfma_f32_16x16x32_bf16 v[34:37], v[174:177], v[198:201], v[34:37]
	v_mfma_f32_16x16x32_bf16 v[22:25], v[166:169], v[206:209], v[22:25]
	v_mfma_f32_16x16x32_bf16 v[18:21], v[174:177], v[206:209], v[18:21]
	v_mfma_f32_16x16x32_bf16 v[6:9], v[166:169], v[214:217], v[6:9]
	v_mfma_f32_16x16x32_bf16 v[2:5], v[174:177], v[214:217], v[2:5]
	s_setprio 0
	s_barrier
; #define PG8_STAGE(bufoff, gbase, voff) do { _Pragma("unroll") for (int _i = 0; _i < 2; ++_i) \
;         __builtin_amdgcn_global_load_lds((const unsigned*)((const char*)(gbase) + (voff)[_i]), (PG8_LAS unsigned*)(lds + (bufoff) + ldsw + _i * 8192), 16, 0, 0); } while (0)
; #define PG8_LDA(dst, b, h) do { _Pragma("unroll") for (int m = 0; m < 4; ++m) _Pragma("unroll") for (int k = 0; k < 2; ++k) dst[m][k] = *(const PG8_LAS bf16x8*)(lds + PG8_SA(b, h) + aoff + m * 2048 + k * 1024); } while (0)
; #define PG8_LDB(dst, b, h) do { _Pragma("unroll") for (int n = 0; n < 2; ++n) _Pragma("unroll") for (int k = 0; k < 2; ++k) dst[n][k] = *(const PG8_LAS bf16x8*)(lds + PG8_SB(b, h) + boff + n * 2048 + k * 1024); } while (0)
; #define PG8_MMA(ai, bj, At, Bt) do { __builtin_amdgcn_s_setprio(1); _Pragma("unroll") for (int m = 0; m < 4; ++m) _Pragma("unroll") for (int n = 0; n < 2; ++n) _Pragma("unroll") for (int k = 0; k < 2; ++k) \
;         acc[ai][bj][m][n] = __builtin_amdgcn_mfma_f32_16x16x32_bf16(Bt[n][k], At[m][k], acc[ai][bj][m][n], 0, 0, 0); __builtin_amdgcn_s_setprio(0); } while (0)
; #define PG8_WAIT_V(n) asm volatile("s_waitcnt vmcnt(" #n ")" ::: "memory")
; #define PG8_WAIT_L(n) asm volatile("s_waitcnt lgkmcnt(" #n ")" ::: "memory")
; #define PG8_BAR __builtin_amdgcn_s_barrier()
; #define PG8_SCHED __builtin_amdgcn_sched_barrier(0)
; template <class Epi, class Sched, bool ALIGN_EPI = false, bool SP2 = false>
; __device__ __forceinline__ void gemm_phase(PG8_LAS unsigned char* lds, const Gemm g, const Sched& S, const Epi& E) {
;     ...
;             PG8_LDB(B0, 1, 0); PG8_LDB(B1, 1, 1); PG8_SCHED; PG8_LDA(At, 1, 0); PG8_STAGE(PG8_SA(0, 1), a2 + hstep, voffA);
;             PG8_WAIT_V(8); PG8_WAIT_L(0); PG8_BAR; PG8_MMA(0, 0, At, B0); PG8_MMA(0, 1, At, B1); PG8_BAR; PG8_SCHED;
;             PG8_LDA(At, 1, 1); PG8_STAGE(PG8_SB(1, 0), b3, voffB); PG8_STAGE(PG8_SB(1, 1), b3 + hstep, voffB); PG8_STAGE(PG8_SA(1, 0), a3, voffA);
;             PG8_WAIT_V(8); PG8_WAIT_L(0); PG8_BAR; PG8_MMA(1, 0, At, B0); PG8_MMA(1, 1, At, B1); PG8_BAR; PG8_SCHED;
	s_add_i32 s20, 0, 0x18000
	v_add_u32_e32 v0, s20, v151
	s_add_i32 s33, 0, 0x1c000
	ds_read_b128 v[142:145], v0
	ds_read_b128 v[146:149], v0 offset:1024
	ds_read_b128 v[154:157], v0 offset:2048
	ds_read_b128 v[158:161], v0 offset:3072
	v_add_u32_e32 v0, s33, v151
	ds_read_b128 v[162:165], v0
	ds_read_b128 v[166:169], v0 offset:1024
	ds_read_b128 v[170:173], v0 offset:2048
	ds_read_b128 v[174:177], v0 offset:3072
	s_add_u32 s2, s26, 0x80000
	s_addc_u32 s3, s27, 0
	s_mov_b32 m0, s67
	ds_read_b128 v[186:189], v153 offset:32768
	ds_read_b128 v[190:193], v153 offset:33792
	ds_read_b128 v[194:197], v153 offset:34816
	ds_read_b128 v[198:201], v153 offset:35840
	ds_read_b128 v[202:205], v153 offset:36864
	ds_read_b128 v[206:209], v153 offset:37888
	ds_read_b128 v[210:213], v153 offset:38912
	ds_read_b128 v[214:217], v153 offset:39936
	global_load_lds_dwordx4 v136, s[2:3]
	s_mov_b32 m0, s72
	s_nop 0
	global_load_lds_dwordx4 v132, s[2:3]
	s_waitcnt vmcnt(8)
	s_waitcnt lgkmcnt(0)
	s_barrier
	s_setprio 1
	s_waitcnt lgkmcnt(0)
	v_mfma_f32_16x16x32_bf16 v[126:129], v[142:145], v[186:189], v[126:129]
	v_mfma_f32_16x16x32_bf16 v[122:125], v[154:157], v[186:189], v[122:125]
	v_mfma_f32_16x16x32_bf16 v[110:113], v[142:145], v[194:197], v[110:113]
	v_mfma_f32_16x16x32_bf16 v[106:109], v[154:157], v[194:197], v[106:109]
	v_mfma_f32_16x16x32_bf16 v[94:97], v[142:145], v[202:205], v[94:97]
	v_mfma_f32_16x16x32_bf16 v[90:93], v[154:157], v[202:205], v[90:93]
	v_mfma_f32_16x16x32_bf16 v[78:81], v[142:145], v[210:213], v[78:81]
	v_mfma_f32_16x16x32_bf16 v[74:77], v[154:157], v[210:213], v[74:77]
	v_mfma_f32_16x16x32_bf16 v[126:129], v[146:149], v[190:193], v[126:129]
	v_mfma_f32_16x16x32_bf16 v[122:125], v[158:161], v[190:193], v[122:125]
	v_mfma_f32_16x16x32_bf16 v[110:113], v[146:149], v[198:201], v[110:113]
	v_mfma_f32_16x16x32_bf16 v[106:109], v[158:161], v[198:201], v[106:109]
	v_mfma_f32_16x16x32_bf16 v[94:97], v[146:149], v[206:209], v[94:97]
	v_mfma_f32_16x16x32_bf16 v[90:93], v[158:161], v[206:209], v[90:93]
	v_mfma_f32_16x16x32_bf16 v[78:81], v[146:149], v[214:217], v[78:81]
	v_mfma_f32_16x16x32_bf16 v[74:77], v[158:161], v[214:217], v[74:77]
	s_setprio 0
	s_setprio 1
	v_mfma_f32_16x16x32_bf16 v[118:121], v[162:165], v[186:189], v[118:121]
	v_mfma_f32_16x16x32_bf16 v[114:117], v[170:173], v[186:189], v[114:117]
	v_mfma_f32_16x16x32_bf16 v[102:105], v[162:165], v[194:197], v[102:105]
	v_mfma_f32_16x16x32_bf16 v[98:101], v[170:173], v[194:197], v[98:101]
	v_mfma_f32_16x16x32_bf16 v[86:89], v[162:165], v[202:205], v[86:89]
	v_mfma_f32_16x16x32_bf16 v[82:85], v[170:173], v[202:205], v[82:85]
	v_mfma_f32_16x16x32_bf16 v[70:73], v[162:165], v[210:213], v[70:73]
	v_mfma_f32_16x16x32_bf16 v[66:69], v[170:173], v[210:213], v[66:69]
	v_mfma_f32_16x16x32_bf16 v[118:121], v[166:169], v[190:193], v[118:121]
	v_mfma_f32_16x16x32_bf16 v[114:117], v[174:177], v[190:193], v[114:117]
	v_mfma_f32_16x16x32_bf16 v[102:105], v[166:169], v[198:201], v[102:105]
	v_mfma_f32_16x16x32_bf16 v[98:101], v[174:177], v[198:201], v[98:101]
	v_mfma_f32_16x16x32_bf16 v[86:89], v[166:169], v[206:209], v[86:89]
	v_mfma_f32_16x16x32_bf16 v[82:85], v[174:177], v[206:209], v[82:85]
	v_mfma_f32_16x16x32_bf16 v[70:73], v[166:169], v[214:217], v[70:73]
	v_mfma_f32_16x16x32_bf16 v[66:69], v[174:177], v[214:217], v[66:69]
	s_setprio 0
	s_barrier
	s_add_i32 s2, s20, s64
	s_add_i32 m0, s2, 0xffffff80
	ds_read_b128 v[186:189], v153 offset:49152
	ds_read_b128 v[190:193], v153 offset:50176
	ds_read_b128 v[194:197], v153 offset:51200
	ds_read_b128 v[198:201], v153 offset:52224
	ds_read_b128 v[202:205], v153 offset:53248
	ds_read_b128 v[206:209], v153 offset:54272
	ds_read_b128 v[210:213], v153 offset:55296
	ds_read_b128 v[214:217], v153 offset:56320
	global_load_lds_dwordx4 v134, s[24:25] offset:128
	s_add_i32 m0, s2, 0x1f80
	s_add_u32 s2, s24, 0x80080
	s_addc_u32 s3, s25, 0
	s_add_i32 s20, s33, s64
	global_load_lds_dwordx4 v130, s[24:25] offset:128
	s_mov_b32 m0, s20
	s_nop 0
	global_load_lds_dwordx4 v134, s[2:3]
	s_add_i32 m0, s20, 0x2000
	s_nop 0
	global_load_lds_dwordx4 v130, s[2:3]
	s_add_i32 m0, s86, 0xffffff80
	s_nop 0
	global_load_lds_dwordx4 v136, s[26:27] offset:128
	s_add_i32 m0, s87, 0xffffff80
	s_nop 0
	global_load_lds_dwordx4 v132, s[26:27] offset:128
	s_waitcnt vmcnt(8)
	s_waitcnt lgkmcnt(0)
	s_barrier
	s_setprio 1
	s_waitcnt lgkmcnt(0)
	v_mfma_f32_16x16x32_bf16 v[62:65], v[142:145], v[186:189], v[62:65]
	v_mfma_f32_16x16x32_bf16 v[58:61], v[154:157], v[186:189], v[58:61]
	v_mfma_f32_16x16x32_bf16 v[46:49], v[142:145], v[194:197], v[46:49]
	v_mfma_f32_16x16x32_bf16 v[42:45], v[154:157], v[194:197], v[42:45]
	v_mfma_f32_16x16x32_bf16 v[30:33], v[142:145], v[202:205], v[30:33]
	v_mfma_f32_16x16x32_bf16 v[26:29], v[154:157], v[202:205], v[26:29]
	v_mfma_f32_16x16x32_bf16 v[14:17], v[142:145], v[210:213], v[14:17]
	v_mfma_f32_16x16x32_bf16 v[10:13], v[154:157], v[210:213], v[10:13]
	v_mfma_f32_16x16x32_bf16 v[62:65], v[146:149], v[190:193], v[62:65]
	v_mfma_f32_16x16x32_bf16 v[58:61], v[158:161], v[190:193], v[58:61]
	v_mfma_f32_16x16x32_bf16 v[46:49], v[146:149], v[198:201], v[46:49]
	v_mfma_f32_16x16x32_bf16 v[42:45], v[158:161], v[198:201], v[42:45]
	v_mfma_f32_16x16x32_bf16 v[30:33], v[146:149], v[206:209], v[30:33]
	v_mfma_f32_16x16x32_bf16 v[26:29], v[158:161], v[206:209], v[26:29]
	v_mfma_f32_16x16x32_bf16 v[14:17], v[146:149], v[214:217], v[14:17]
	v_mfma_f32_16x16x32_bf16 v[10:13], v[158:161], v[214:217], v[10:13]
	s_setprio 0
	s_setprio 1
	v_mfma_f32_16x16x32_bf16 v[54:57], v[162:165], v[186:189], v[54:57]
	v_mfma_f32_16x16x32_bf16 v[50:53], v[170:173], v[186:189], v[50:53]
	v_mfma_f32_16x16x32_bf16 v[38:41], v[162:165], v[194:197], v[38:41]
	v_mfma_f32_16x16x32_bf16 v[34:37], v[170:173], v[194:197], v[34:37]
	v_mfma_f32_16x16x32_bf16 v[22:25], v[162:165], v[202:205], v[22:25]
	v_mfma_f32_16x16x32_bf16 v[18:21], v[170:173], v[202:205], v[18:21]
	v_mfma_f32_16x16x32_bf16 v[6:9], v[162:165], v[210:213], v[6:9]
	v_mfma_f32_16x16x32_bf16 v[2:5], v[170:173], v[210:213], v[2:5]
	v_mfma_f32_16x16x32_bf16 v[54:57], v[166:169], v[190:193], v[54:57]
	v_mfma_f32_16x16x32_bf16 v[50:53], v[174:177], v[190:193], v[50:53]
	v_mfma_f32_16x16x32_bf16 v[38:41], v[166:169], v[198:201], v[38:41]
	v_mfma_f32_16x16x32_bf16 v[34:37], v[174:177], v[198:201], v[34:37]
	v_mfma_f32_16x16x32_bf16 v[22:25], v[166:169], v[206:209], v[22:25]
	v_mfma_f32_16x16x32_bf16 v[18:21], v[174:177], v[206:209], v[18:21]
	v_mfma_f32_16x16x32_bf16 v[6:9], v[166:169], v[214:217], v[6:9]
	v_mfma_f32_16x16x32_bf16 v[2:5], v[174:177], v[214:217], v[2:5]
	s_setprio 0
	s_barrier
	s_add_i32 s53, s53, 2
	s_add_u32 s9, s9, 0x100
	s_addc_u32 s30, s30, 0
	s_add_u32 s12, s12, 0x100
	s_addc_u32 s13, s13, 0
	s_cmp_gt_u32 s53, 29
	s_cbranch_scc0 .LBB0_309
	s_and_b64 vcc, exec, s[50:51]
	s_cbranch_vccz .LBB0_312
	s_barrier

; #define PG8_STAGE(bufoff, gbase, voff) do { _Pragma("unroll") for (int _i = 0; _i < 2; ++_i) \
;         __builtin_amdgcn_global_load_lds((const unsigned*)((const char*)(gbase) + (voff)[_i]), (PG8_LAS unsigned*)(lds + (bufoff) + ldsw + _i * 8192), 16, 0, 0); } while (0)
; #define PG8_LDA(dst, b, h) do { _Pragma("unroll") for (int m = 0; m < 4; ++m) _Pragma("unroll") for (int k = 0; k < 2; ++k) dst[m][k] = *(const PG8_LAS bf16x8*)(lds + PG8_SA(b, h) + aoff + m * 2048 + k * 1024); } while (0)
; #define PG8_LDB(dst, b, h) do { _Pragma("unroll") for (int n = 0; n < 2; ++n) _Pragma("unroll") for (int k = 0; k < 2; ++k) dst[n][k] = *(const PG8_LAS bf16x8*)(lds + PG8_SB(b, h) + boff + n * 2048 + k * 1024); } while (0)
; #define PG8_MMA(ai, bj, At, Bt) do { __builtin_amdgcn_s_setprio(1); _Pragma("unroll") for (int m = 0; m < 4; ++m) _Pragma("unroll") for (int n = 0; n < 2; ++n) _Pragma("unroll") for (int k = 0; k < 2; ++k) \
;         acc[ai][bj][m][n] = __builtin_amdgcn_mfma_f32_16x16x32_bf16(Bt[n][k], At[m][k], acc[ai][bj][m][n], 0, 0, 0); __builtin_amdgcn_s_setprio(0); } while (0)
; #define PG8_WAIT_V(n) asm volatile("s_waitcnt vmcnt(" #n ")" ::: "memory")
; #define PG8_WAIT_L(n) asm volatile("s_waitcnt lgkmcnt(" #n ")" ::: "memory")
; #define PG8_BAR __builtin_amdgcn_s_barrier()
; template <class Epi, class Sched, bool ALIGN_EPI = false, bool SP2 = false>
; __device__ __forceinline__ void gemm_phase(PG8_LAS unsigned char* lds, const Gemm g, const Sched& S, const Epi& E) {
;     ...
;             const char* a1 = cA + (size_t)(t + 1) * kstep;
;             const char* a2 = last ? nA : cA + (size_t)(t + 2) * kstep; const char* b2 = last ? nB : cB + (size_t)(t + 2) * kstep;
;             const char* a3 = a2 + kstep; const char* b3 = b2 + kstep;
;             if (last && has_next) S.a_ready(nxt);
;             if constexpr (SP2) {
;             PG8_LDB(B0, 0, 0); PG8_LDB(B1, 0, 1); PG8_SCHED; PG8_LDA(At, 0, 0); PG8_STAGE(PG8_SA(1, 1), a1 + hstep, voffA);
;             PG8_WAIT_V(8); PG8_WAIT_L(0); PG8_BAR; PG8_MMA(0, 0, At, B0); PG8_MMA(0, 1, At, B1); PG8_BAR; PG8_SCHED;
;             PG8_LDA(At, 0, 1); PG8_STAGE(PG8_SB(0, 0), b2, voffB); PG8_STAGE(PG8_SB(0, 1), b2 + hstep, voffB); PG8_STAGE(PG8_SA(0, 0), a2, voffA);
;             PG8_WAIT_V(8); PG8_WAIT_L(0); PG8_BAR; PG8_MMA(1, 0, At, B0); PG8_MMA(1, 1, At, B1); PG8_BAR; PG8_SCHED;
.LBB0_351:
	s_add_u32 s2, s12, 0xfff80080
	s_addc_u32 s3, s13, -1
	s_add_i32 s20, 0, 0x10000
	s_cmp_eq_u32 s51, 28
	s_cselect_b32 s43, s5, s3
	s_cselect_b32 s42, s6, s2
	v_add_u32_e32 v0, s20, v169
	s_cselect_b32 s25, s7, s49
	s_cselect_b32 s24, s8, s9
	s_add_i32 s33, 0, 0x14000
	ds_read_b128 v[2:5], v0
	ds_read_b128 v[6:9], v0 offset:1024
	ds_read_b128 v[138:141], v0 offset:2048
	ds_read_b128 v[142:145], v0 offset:3072
	v_add_u32_e32 v0, s33, v169
	ds_read_b128 v[164:167], v0
	ds_read_b128 v[174:177], v0 offset:1024
	ds_read_b128 v[186:189], v0 offset:2048
	ds_read_b128 v[190:193], v0 offset:3072
	s_add_i32 m0, s58, 0xc000
	ds_read_b128 v[194:197], v172
	ds_read_b128 v[198:201], v172 offset:1024
	ds_read_b128 v[202:205], v172 offset:2048
	ds_read_b128 v[206:209], v172 offset:3072
	ds_read_b128 v[210:213], v172 offset:4096
	ds_read_b128 v[214:217], v172 offset:5120
	ds_read_b128 v[218:221], v172 offset:6144
	ds_read_b128 v[222:225], v172 offset:7168
	global_load_lds_dwordx4 v160, s[12:13]
	s_add_i32 m0, s58, 0xe000
	s_nop 0
	global_load_lds_dwordx4 v158, s[12:13]
	s_waitcnt vmcnt(8)
	s_waitcnt lgkmcnt(0)
	s_barrier
	s_setprio 1
	s_waitcnt lgkmcnt(0)
	v_mfma_f32_16x16x32_bf16 v[134:137], v[2:5], v[194:197], v[134:137]
	v_mfma_f32_16x16x32_bf16 v[130:133], v[138:141], v[194:197], v[130:133]
	v_mfma_f32_16x16x32_bf16 v[118:121], v[2:5], v[202:205], v[118:121]
	v_mfma_f32_16x16x32_bf16 v[114:117], v[138:141], v[202:205], v[114:117]
	v_mfma_f32_16x16x32_bf16 v[102:105], v[2:5], v[210:213], v[102:105]
	v_mfma_f32_16x16x32_bf16 v[98:101], v[138:141], v[210:213], v[98:101]
	v_mfma_f32_16x16x32_bf16 v[86:89], v[2:5], v[218:221], v[86:89]
	v_mfma_f32_16x16x32_bf16 v[82:85], v[138:141], v[218:221], v[82:85]
	v_mfma_f32_16x16x32_bf16 v[134:137], v[6:9], v[198:201], v[134:137]
	v_mfma_f32_16x16x32_bf16 v[130:133], v[142:145], v[198:201], v[130:133]
	v_mfma_f32_16x16x32_bf16 v[118:121], v[6:9], v[206:209], v[118:121]
	v_mfma_f32_16x16x32_bf16 v[114:117], v[142:145], v[206:209], v[114:117]
	v_mfma_f32_16x16x32_bf16 v[102:105], v[6:9], v[214:217], v[102:105]
	v_mfma_f32_16x16x32_bf16 v[98:101], v[142:145], v[214:217], v[98:101]
	v_mfma_f32_16x16x32_bf16 v[86:89], v[6:9], v[222:225], v[86:89]
	v_mfma_f32_16x16x32_bf16 v[82:85], v[142:145], v[222:225], v[82:85]
	s_setprio 0
	s_setprio 1
	v_mfma_f32_16x16x32_bf16 v[126:129], v[164:167], v[194:197], v[126:129]
	v_mfma_f32_16x16x32_bf16 v[122:125], v[186:189], v[194:197], v[122:125]
	v_mfma_f32_16x16x32_bf16 v[110:113], v[164:167], v[202:205], v[110:113]
	v_mfma_f32_16x16x32_bf16 v[106:109], v[186:189], v[202:205], v[106:109]
	v_mfma_f32_16x16x32_bf16 v[94:97], v[164:167], v[210:213], v[94:97]
	v_mfma_f32_16x16x32_bf16 v[90:93], v[186:189], v[210:213], v[90:93]
	v_mfma_f32_16x16x32_bf16 v[78:81], v[164:167], v[218:221], v[78:81]
	v_mfma_f32_16x16x32_bf16 v[74:77], v[186:189], v[218:221], v[74:77]
	v_mfma_f32_16x16x32_bf16 v[126:129], v[174:177], v[198:201], v[126:129]
	v_mfma_f32_16x16x32_bf16 v[122:125], v[190:193], v[198:201], v[122:125]
	v_mfma_f32_16x16x32_bf16 v[110:113], v[174:177], v[206:209], v[110:113]
	v_mfma_f32_16x16x32_bf16 v[106:109], v[190:193], v[206:209], v[106:109]
	v_mfma_f32_16x16x32_bf16 v[94:97], v[174:177], v[214:217], v[94:97]
	v_mfma_f32_16x16x32_bf16 v[90:93], v[190:193], v[214:217], v[90:93]
	v_mfma_f32_16x16x32_bf16 v[78:81], v[174:177], v[222:225], v[78:81]
	v_mfma_f32_16x16x32_bf16 v[74:77], v[190:193], v[222:225], v[74:77]
	s_setprio 0
	s_barrier
	s_add_i32 s2, s20, s57
	s_mov_b32 m0, s2
	ds_read_b128 v[194:197], v172 offset:16384
	ds_read_b128 v[198:201], v172 offset:17408
	ds_read_b128 v[202:205], v172 offset:18432
	ds_read_b128 v[206:209], v172 offset:19456
	ds_read_b128 v[210:213], v172 offset:20480
	ds_read_b128 v[214:217], v172 offset:21504
	ds_read_b128 v[218:221], v172 offset:22528
	ds_read_b128 v[222:225], v172 offset:23552
	global_load_lds_dwordx4 v150, s[24:25]
	s_add_i32 m0, s2, 0x2000
	s_add_u32 s2, s24, 0x80000
	s_addc_u32 s3, s25, 0
	s_add_i32 s20, s33, s57
	global_load_lds_dwordx4 v146, s[24:25]
	s_mov_b32 m0, s20
	s_nop 0
	global_load_lds_dwordx4 v150, s[2:3]
	s_add_i32 m0, s20, 0x2000
	s_nop 0
	global_load_lds_dwordx4 v146, s[2:3]
	s_mov_b32 m0, s58
	s_nop 0
	global_load_lds_dwordx4 v152, s[42:43]
	s_mov_b32 m0, s59
	s_nop 0
	global_load_lds_dwordx4 v148, s[42:43]
	s_waitcnt vmcnt(8)
	s_waitcnt lgkmcnt(0)
	s_barrier
	s_setprio 1
	s_waitcnt lgkmcnt(0)
	v_mfma_f32_16x16x32_bf16 v[70:73], v[2:5], v[194:197], v[70:73]
	v_mfma_f32_16x16x32_bf16 v[66:69], v[138:141], v[194:197], v[66:69]
	v_mfma_f32_16x16x32_bf16 v[54:57], v[2:5], v[202:205], v[54:57]
	v_mfma_f32_16x16x32_bf16 v[50:53], v[138:141], v[202:205], v[50:53]
	v_mfma_f32_16x16x32_bf16 v[38:41], v[2:5], v[210:213], v[38:41]
	v_mfma_f32_16x16x32_bf16 v[34:37], v[138:141], v[210:213], v[34:37]
	v_mfma_f32_16x16x32_bf16 v[2:5], v[2:5], v[218:221], v[22:25]
	v_mfma_f32_16x16x32_bf16 v[70:73], v[6:9], v[198:201], v[70:73]
	v_mfma_f32_16x16x32_bf16 v[66:69], v[142:145], v[198:201], v[66:69]
	v_mfma_f32_16x16x32_bf16 v[54:57], v[6:9], v[206:209], v[54:57]
	v_mfma_f32_16x16x32_bf16 v[50:53], v[142:145], v[206:209], v[50:53]
	v_mfma_f32_16x16x32_bf16 v[38:41], v[6:9], v[214:217], v[38:41]
	v_mfma_f32_16x16x32_bf16 v[34:37], v[142:145], v[214:217], v[34:37]
	v_mfma_f32_16x16x32_bf16 v[2:5], v[6:9], v[222:225], v[2:5]
	v_mfma_f32_16x16x32_bf16 v[6:9], v[138:141], v[218:221], v[18:21]
	v_mfma_f32_16x16x32_bf16 v[6:9], v[142:145], v[222:225], v[6:9]
	s_setprio 0
	s_setprio 1
	v_mfma_f32_16x16x32_bf16 v[18:21], v[164:167], v[194:197], v[62:65]
	v_mfma_f32_16x16x32_bf16 v[62:65], v[174:177], v[198:201], v[18:21]
	v_mfma_f32_16x16x32_bf16 v[18:21], v[186:189], v[194:197], v[58:61]
	v_mfma_f32_16x16x32_bf16 v[58:61], v[190:193], v[198:201], v[18:21]
	v_mfma_f32_16x16x32_bf16 v[18:21], v[164:167], v[202:205], v[46:49]
	v_mfma_f32_16x16x32_bf16 v[46:49], v[174:177], v[206:209], v[18:21]
	v_mfma_f32_16x16x32_bf16 v[18:21], v[186:189], v[202:205], v[42:45]
	v_mfma_f32_16x16x32_bf16 v[42:45], v[190:193], v[206:209], v[18:21]
	v_mfma_f32_16x16x32_bf16 v[18:21], v[164:167], v[210:213], v[30:33]
	v_mfma_f32_16x16x32_bf16 v[30:33], v[174:177], v[214:217], v[18:21]
	v_mfma_f32_16x16x32_bf16 v[18:21], v[186:189], v[210:213], v[26:29]
	v_mfma_f32_16x16x32_bf16 v[14:17], v[164:167], v[218:221], v[14:17]
	v_mfma_f32_16x16x32_bf16 v[10:13], v[186:189], v[218:221], v[10:13]
	v_mfma_f32_16x16x32_bf16 v[26:29], v[190:193], v[214:217], v[18:21]
	v_mfma_f32_16x16x32_bf16 v[14:17], v[174:177], v[222:225], v[14:17]
	v_mfma_f32_16x16x32_bf16 v[10:13], v[190:193], v[222:225], v[10:13]
	s_setprio 0
	s_barrier
; #define PG8_STAGE(bufoff, gbase, voff) do { _Pragma("unroll") for (int _i = 0; _i < 2; ++_i) \
;         __builtin_amdgcn_global_load_lds((const unsigned*)((const char*)(gbase) + (voff)[_i]), (PG8_LAS unsigned*)(lds + (bufoff) + ldsw + _i * 8192), 16, 0, 0); } while (0)
; #define PG8_LDA(dst, b, h) do { _Pragma("unroll") for (int m = 0; m < 4; ++m) _Pragma("unroll") for (int k = 0; k < 2; ++k) dst[m][k] = *(const PG8_LAS bf16x8*)(lds + PG8_SA(b, h) + aoff + m * 2048 + k * 1024); } while (0)
; #define PG8_LDB(dst, b, h) do { _Pragma("unroll") for (int n = 0; n < 2; ++n) _Pragma("unroll") for (int k = 0; k < 2; ++k) dst[n][k] = *(const PG8_LAS bf16x8*)(lds + PG8_SB(b, h) + boff + n * 2048 + k * 1024); } while (0)
; #define PG8_MMA(ai, bj, At, Bt) do { __builtin_amdgcn_s_setprio(1); _Pragma("unroll") for (int m = 0; m < 4; ++m) _Pragma("unroll") for (int n = 0; n < 2; ++n) _Pragma("unroll") for (int k = 0; k < 2; ++k) \
;         acc[ai][bj][m][n] = __builtin_amdgcn_mfma_f32_16x16x32_bf16(Bt[n][k], At[m][k], acc[ai][bj][m][n], 0, 0, 0); __builtin_amdgcn_s_setprio(0); } while (0)
; #define PG8_WAIT_V(n) asm volatile("s_waitcnt vmcnt(" #n ")" ::: "memory")
; #define PG8_WAIT_L(n) asm volatile("s_waitcnt lgkmcnt(" #n ")" ::: "memory")
; #define PG8_BAR __builtin_amdgcn_s_barrier()
; #define PG8_SCHED __builtin_amdgcn_sched_barrier(0)
; template <class Epi, class Sched, bool ALIGN_EPI = false, bool SP2 = false>
; __device__ __forceinline__ void gemm_phase(PG8_LAS unsigned char* lds, const Gemm g, const Sched& S, const Epi& E) {
;     ...
;             PG8_LDB(B0, 1, 0); PG8_LDB(B1, 1, 1); PG8_SCHED; PG8_LDA(At, 1, 0); PG8_STAGE(PG8_SA(0, 1), a2 + hstep, voffA);
;             PG8_WAIT_V(8); PG8_WAIT_L(0); PG8_BAR; PG8_MMA(0, 0, At, B0); PG8_MMA(0, 1, At, B1); PG8_BAR; PG8_SCHED;
;             PG8_LDA(At, 1, 1); PG8_STAGE(PG8_SB(1, 0), b3, voffB); PG8_STAGE(PG8_SB(1, 1), b3 + hstep, voffB); PG8_STAGE(PG8_SA(1, 0), a3, voffA);
;             PG8_WAIT_V(8); PG8_WAIT_L(0); PG8_BAR; PG8_MMA(1, 0, At, B0); PG8_MMA(1, 1, At, B1); PG8_BAR; PG8_SCHED;
;     __device__ __forceinline__ void operator()(const f32x4 (&acc)[2][2][4][2], const Unit& u, int wr, int wc, int fr, int fq) const {
;     ...
;         if (pn < 8) {
;             bf16_t* dst = pn < 4 ? q : k; const float sc = pn < 4 ? QSCALE : 1.f;
;             const int head = (pn & 3) * 2 + (wc >> 1), i0 = 32 * (wc & 1) + 8 * fq;
	s_add_i32 s20, 0, 0x18000
	v_add_u32_e32 v0, s20, v169
	s_add_i32 s33, 0, 0x1c000
	ds_read_b128 v[18:21], v0
	ds_read_b128 v[22:25], v0 offset:1024
	ds_read_b128 v[138:141], v0 offset:2048
	ds_read_b128 v[142:145], v0 offset:3072
	v_add_u32_e32 v0, s33, v169
	ds_read_b128 v[164:167], v0
	ds_read_b128 v[174:177], v0 offset:1024
	ds_read_b128 v[186:189], v0 offset:2048
	ds_read_b128 v[190:193], v0 offset:3072
	s_add_u32 s2, s42, 0x80000
	s_addc_u32 s3, s43, 0
	s_mov_b32 m0, s60
	ds_read_b128 v[194:197], v172 offset:32768
	ds_read_b128 v[198:201], v172 offset:33792
	ds_read_b128 v[202:205], v172 offset:34816
	ds_read_b128 v[206:209], v172 offset:35840
	ds_read_b128 v[210:213], v172 offset:36864
	ds_read_b128 v[214:217], v172 offset:37888
	ds_read_b128 v[218:221], v172 offset:38912
	ds_read_b128 v[222:225], v172 offset:39936
	global_load_lds_dwordx4 v152, s[2:3]
	s_mov_b32 m0, s61
	s_nop 0
	global_load_lds_dwordx4 v148, s[2:3]
	s_waitcnt vmcnt(8)
	s_waitcnt lgkmcnt(0)
	s_barrier
	s_setprio 1
	s_waitcnt lgkmcnt(0)
	v_mfma_f32_16x16x32_bf16 v[134:137], v[18:21], v[194:197], v[134:137]
	v_mfma_f32_16x16x32_bf16 v[130:133], v[138:141], v[194:197], v[130:133]
	v_mfma_f32_16x16x32_bf16 v[118:121], v[18:21], v[202:205], v[118:121]
	v_mfma_f32_16x16x32_bf16 v[114:117], v[138:141], v[202:205], v[114:117]
	v_mfma_f32_16x16x32_bf16 v[102:105], v[18:21], v[210:213], v[102:105]
	v_mfma_f32_16x16x32_bf16 v[98:101], v[138:141], v[210:213], v[98:101]
	v_mfma_f32_16x16x32_bf16 v[86:89], v[18:21], v[218:221], v[86:89]
	v_mfma_f32_16x16x32_bf16 v[82:85], v[138:141], v[218:221], v[82:85]
	v_mfma_f32_16x16x32_bf16 v[134:137], v[22:25], v[198:201], v[134:137]
	v_mfma_f32_16x16x32_bf16 v[130:133], v[142:145], v[198:201], v[130:133]
	v_mfma_f32_16x16x32_bf16 v[118:121], v[22:25], v[206:209], v[118:121]
	v_mfma_f32_16x16x32_bf16 v[114:117], v[142:145], v[206:209], v[114:117]
	v_mfma_f32_16x16x32_bf16 v[102:105], v[22:25], v[214:217], v[102:105]
	v_mfma_f32_16x16x32_bf16 v[98:101], v[142:145], v[214:217], v[98:101]
	v_mfma_f32_16x16x32_bf16 v[86:89], v[22:25], v[222:225], v[86:89]
	v_mfma_f32_16x16x32_bf16 v[82:85], v[142:145], v[222:225], v[82:85]
	s_setprio 0
	s_setprio 1
	v_mfma_f32_16x16x32_bf16 v[126:129], v[164:167], v[194:197], v[126:129]
	v_mfma_f32_16x16x32_bf16 v[122:125], v[186:189], v[194:197], v[122:125]
	v_mfma_f32_16x16x32_bf16 v[110:113], v[164:167], v[202:205], v[110:113]
	v_mfma_f32_16x16x32_bf16 v[106:109], v[186:189], v[202:205], v[106:109]
	v_mfma_f32_16x16x32_bf16 v[94:97], v[164:167], v[210:213], v[94:97]
	v_mfma_f32_16x16x32_bf16 v[90:93], v[186:189], v[210:213], v[90:93]
	v_mfma_f32_16x16x32_bf16 v[78:81], v[164:167], v[218:221], v[78:81]
	v_mfma_f32_16x16x32_bf16 v[74:77], v[186:189], v[218:221], v[74:77]
	v_mfma_f32_16x16x32_bf16 v[126:129], v[174:177], v[198:201], v[126:129]
	v_mfma_f32_16x16x32_bf16 v[122:125], v[190:193], v[198:201], v[122:125]
	v_mfma_f32_16x16x32_bf16 v[110:113], v[174:177], v[206:209], v[110:113]
	v_mfma_f32_16x16x32_bf16 v[106:109], v[190:193], v[206:209], v[106:109]
	v_mfma_f32_16x16x32_bf16 v[94:97], v[174:177], v[214:217], v[94:97]
	v_mfma_f32_16x16x32_bf16 v[90:93], v[190:193], v[214:217], v[90:93]
	v_mfma_f32_16x16x32_bf16 v[78:81], v[174:177], v[222:225], v[78:81]
	v_mfma_f32_16x16x32_bf16 v[74:77], v[190:193], v[222:225], v[74:77]
	s_setprio 0
	s_barrier
	s_add_i32 s2, s20, s57
	s_add_i32 m0, s2, 0xffffff80
	ds_read_b128 v[194:197], v172 offset:49152
	ds_read_b128 v[198:201], v172 offset:50176
	ds_read_b128 v[202:205], v172 offset:51200
	ds_read_b128 v[206:209], v172 offset:52224
	ds_read_b128 v[210:213], v172 offset:53248
	ds_read_b128 v[214:217], v172 offset:54272
	ds_read_b128 v[218:221], v172 offset:55296
	ds_read_b128 v[222:225], v172 offset:56320
	global_load_lds_dwordx4 v150, s[24:25] offset:128
	s_add_i32 m0, s2, 0x1f80
	s_add_u32 s2, s24, 0x80080
	s_addc_u32 s3, s25, 0
	s_add_i32 s20, s33, s57
	global_load_lds_dwordx4 v146, s[24:25] offset:128
	s_mov_b32 m0, s20
	s_nop 0
	global_load_lds_dwordx4 v150, s[2:3]
	s_add_i32 m0, s20, 0x2000
	s_nop 0
	global_load_lds_dwordx4 v146, s[2:3]
	s_add_i32 m0, s64, 0xffffff80
	s_nop 0
	global_load_lds_dwordx4 v152, s[42:43] offset:128
	s_add_i32 m0, s65, 0xffffff80
	s_nop 0
	global_load_lds_dwordx4 v148, s[42:43] offset:128
	s_waitcnt vmcnt(8)
	s_waitcnt lgkmcnt(0)
	s_barrier
	s_setprio 1
	s_waitcnt lgkmcnt(0)
	v_mfma_f32_16x16x32_bf16 v[70:73], v[18:21], v[194:197], v[70:73]
	v_mfma_f32_16x16x32_bf16 v[54:57], v[18:21], v[202:205], v[54:57]
	v_mfma_f32_16x16x32_bf16 v[38:41], v[18:21], v[210:213], v[38:41]
	v_mfma_f32_16x16x32_bf16 v[2:5], v[18:21], v[218:221], v[2:5]
	v_mfma_f32_16x16x32_bf16 v[70:73], v[22:25], v[198:201], v[70:73]
	v_mfma_f32_16x16x32_bf16 v[66:69], v[138:141], v[194:197], v[66:69]
	v_mfma_f32_16x16x32_bf16 v[54:57], v[22:25], v[206:209], v[54:57]
	v_mfma_f32_16x16x32_bf16 v[50:53], v[138:141], v[202:205], v[50:53]
	v_mfma_f32_16x16x32_bf16 v[38:41], v[22:25], v[214:217], v[38:41]
	v_mfma_f32_16x16x32_bf16 v[34:37], v[138:141], v[210:213], v[34:37]
	v_mfma_f32_16x16x32_bf16 v[22:25], v[22:25], v[222:225], v[2:5]
	v_mfma_f32_16x16x32_bf16 v[2:5], v[138:141], v[218:221], v[6:9]
	v_mfma_f32_16x16x32_bf16 v[66:69], v[142:145], v[198:201], v[66:69]
	v_mfma_f32_16x16x32_bf16 v[50:53], v[142:145], v[206:209], v[50:53]
	v_mfma_f32_16x16x32_bf16 v[34:37], v[142:145], v[214:217], v[34:37]
	v_mfma_f32_16x16x32_bf16 v[18:21], v[142:145], v[222:225], v[2:5]
	s_setprio 0
	s_setprio 1
	v_mfma_f32_16x16x32_bf16 v[2:5], v[164:167], v[194:197], v[62:65]
	v_mfma_f32_16x16x32_bf16 v[62:65], v[174:177], v[198:201], v[2:5]
	v_mfma_f32_16x16x32_bf16 v[2:5], v[186:189], v[194:197], v[58:61]
	v_mfma_f32_16x16x32_bf16 v[58:61], v[190:193], v[198:201], v[2:5]
	v_mfma_f32_16x16x32_bf16 v[2:5], v[164:167], v[202:205], v[46:49]
	v_mfma_f32_16x16x32_bf16 v[46:49], v[174:177], v[206:209], v[2:5]
	v_mfma_f32_16x16x32_bf16 v[2:5], v[186:189], v[202:205], v[42:45]
	v_mfma_f32_16x16x32_bf16 v[42:45], v[190:193], v[206:209], v[2:5]
	v_mfma_f32_16x16x32_bf16 v[2:5], v[164:167], v[210:213], v[30:33]
	v_mfma_f32_16x16x32_bf16 v[30:33], v[174:177], v[214:217], v[2:5]
	v_mfma_f32_16x16x32_bf16 v[2:5], v[186:189], v[210:213], v[26:29]
	v_mfma_f32_16x16x32_bf16 v[26:29], v[190:193], v[214:217], v[2:5]
	v_mfma_f32_16x16x32_bf16 v[2:5], v[164:167], v[218:221], v[14:17]
	v_mfma_f32_16x16x32_bf16 v[14:17], v[174:177], v[222:225], v[2:5]
	v_mfma_f32_16x16x32_bf16 v[2:5], v[186:189], v[218:221], v[10:13]
	v_mfma_f32_16x16x32_bf16 v[10:13], v[190:193], v[222:225], v[2:5]
	s_setprio 0
	s_barrier
	s_add_i32 s51, s51, 2
	s_add_u32 s9, s9, 0x100
	s_addc_u32 s49, s49, 0
	s_add_u32 s12, s12, 0x100
	s_addc_u32 s13, s13, 0
	s_cmp_gt_u32 s51, 29
	s_cbranch_scc0 .LBB0_351
	s_and_b64 vcc, exec, s[26:27]
	s_cbranch_vccz .LBB0_356
	s_barrier
	v_lshl_add_u32 v164, s4, 8, v168
	s_cmp_gt_i32 s72, 7
	s_mov_b64 s[12:13], -1
	s_cbranch_scc1 .LBB0_357
